# P4 LN statistics group 0 rewritten with packed f32 + permlane swaps (replaces hipcc's ds_bpermute version)
# speedup vs baseline: 1.0073x; 1.0073x over previous
.Lst_e5:
	s_or_b64 exec, exec, s[8:9]
	s_waitcnt vmcnt(4)
	s_nop 0
	v_cndmask_b32_e64 v189, v144, v136, s[0:1]
	v_mov_b32_e32 v190, v169
	v_cndmask_b32_e64 v188, v145, v137, s[0:1]
	v_cndmask_b32_e64 v187, v146, v138, s[0:1]
	v_mov_b32_dpp v190, v189 row_ror:8 row_mask:0xf bank_mask:0xf
	v_mov_b32_e32 v189, v169
	v_cndmask_b32_e64 v144, v190, v144, s[0:1]
	v_cndmask_b32_e64 v136, v136, v190, s[0:1]
	v_mov_b32_dpp v189, v188 row_ror:8 row_mask:0xf bank_mask:0xf
	v_cndmask_b32_e64 v145, v189, v145, s[0:1]
	v_cndmask_b32_e64 v137, v137, v189, s[0:1]
	v_mov_b32_e32 v188, v169
	v_pk_fma_f32 v[40:41], v[144:145], s[28:29], v[40:41] op_sel_hi:[1,0,1]
	v_pk_fma_f32 v[44:45], v[136:137], s[28:29], v[44:45] op_sel_hi:[1,0,1]
	v_cndmask_b32_e64 v136, v140, v132, s[0:1]
	v_mov_b32_e32 v144, v169
	v_cndmask_b32_e64 v186, v147, v139, s[0:1]
	v_mov_b32_dpp v188, v187 row_ror:8 row_mask:0xf bank_mask:0xf
	v_mov_b32_e32 v187, v169
	v_mov_b32_dpp v144, v136 row_ror:8 row_mask:0xf bank_mask:0xf
	v_cndmask_b32_e64 v137, v141, v133, s[0:1]
	v_mov_b32_dpp v187, v186 row_ror:8 row_mask:0xf bank_mask:0xf
	v_cndmask_b32_e64 v136, v144, v140, s[0:1]
	v_mov_b32_e32 v140, v169
	v_cndmask_b32_e64 v138, v138, v188, s[0:1]
	v_cndmask_b32_e64 v139, v139, v187, s[0:1]
	v_mov_b32_dpp v140, v137 row_ror:8 row_mask:0xf bank_mask:0xf
	v_pk_fma_f32 v[46:47], v[138:139], s[28:29], v[46:47] op_sel_hi:[1,0,1]
	v_cndmask_b32_e64 v138, v142, v134, s[0:1]
	v_cndmask_b32_e64 v137, v140, v141, s[0:1]
	v_cndmask_b32_e64 v133, v133, v140, s[0:1]
	v_mov_b32_e32 v140, v169
	v_cndmask_b32_e64 v139, v143, v135, s[0:1]
	v_cndmask_b32_e64 v132, v132, v144, s[0:1]
	v_mov_b32_dpp v140, v138 row_ror:8 row_mask:0xf bank_mask:0xf
	v_cndmask_b32_e64 v138, v140, v142, s[0:1]
	v_cndmask_b32_e64 v134, v134, v140, s[0:1]
	v_mov_b32_e32 v140, v169
	s_waitcnt vmcnt(0)
	v_pk_fma_f32 v[36:37], v[132:133], s[28:29], v[36:37] op_sel_hi:[1,0,1]
	v_cndmask_b32_e64 v133, v157, v149, s[0:1]
	v_mov_b32_dpp v140, v139 row_ror:8 row_mask:0xf bank_mask:0xf
	v_cndmask_b32_e64 v135, v135, v140, s[0:1]
	v_pk_fma_f32 v[38:39], v[134:135], s[28:29], v[38:39] op_sel_hi:[1,0,1]
	v_cndmask_b32_e64 v132, v156, v148, s[0:1]
	v_mov_b32_e32 v134, v169
	v_mov_b32_e32 v135, v169
	v_cndmask_b32_e64 v139, v140, v143, s[0:1]
	v_mov_b32_dpp v134, v132 row_ror:8 row_mask:0xf bank_mask:0xf
	v_mov_b32_dpp v135, v133 row_ror:8 row_mask:0xf bank_mask:0xf
	v_cndmask_b32_e64 v132, v134, v156, s[0:1]
	v_cndmask_b32_e64 v134, v148, v134, s[0:1]
	v_cndmask_b32_e64 v133, v135, v157, s[0:1]
	v_cndmask_b32_e64 v135, v149, v135, s[0:1]
	v_pk_fma_f32 v[48:49], v[132:133], s[28:29], v[48:49] op_sel_hi:[1,0,1]
	v_pk_fma_f32 v[52:53], v[134:135], s[28:29], v[52:53] op_sel_hi:[1,0,1]
	v_cndmask_b32_e64 v132, v152, v128, s[0:1]
	v_mov_b32_e32 v134, v169
	v_pk_fma_f32 v[34:35], v[138:139], s[28:29], v[34:35] op_sel_hi:[1,0,1]
	v_pk_fma_f32 v[32:33], v[136:137], s[28:29], v[32:33] op_sel_hi:[1,0,1]
	v_cndmask_b32_e64 v137, v159, v151, s[0:1]
	v_cndmask_b32_e64 v136, v158, v150, s[0:1]
	v_mov_b32_e32 v138, v169
	v_mov_b32_e32 v139, v169
	v_mov_b32_dpp v134, v132 row_ror:8 row_mask:0xf bank_mask:0xf
	v_mov_b32_dpp v138, v136 row_ror:8 row_mask:0xf bank_mask:0xf
	v_mov_b32_dpp v139, v137 row_ror:8 row_mask:0xf bank_mask:0xf
	v_cndmask_b32_e64 v133, v153, v129, s[0:1]
	v_cndmask_b32_e64 v132, v134, v152, s[0:1]
	v_cndmask_b32_e64 v134, v128, v134, s[0:1]
	v_mov_b32_e32 v128, v169
	v_cndmask_b32_e64 v136, v138, v158, s[0:1]
	v_cndmask_b32_e64 v137, v139, v159, s[0:1]
	v_mov_b32_dpp v128, v133 row_ror:8 row_mask:0xf bank_mask:0xf
	v_cndmask_b32_e64 v138, v150, v138, s[0:1]
	v_cndmask_b32_e64 v139, v151, v139, s[0:1]
	v_pk_fma_f32 v[50:51], v[136:137], s[28:29], v[50:51] op_sel_hi:[1,0,1]
	v_cndmask_b32_e64 v136, v154, v130, s[0:1]
	v_cndmask_b32_e64 v133, v128, v153, s[0:1]
	v_cndmask_b32_e64 v135, v129, v128, s[0:1]
	v_mov_b32_e32 v128, v169
	v_cndmask_b32_e64 v146, v188, v146, s[0:1]
	v_cndmask_b32_e64 v147, v187, v147, s[0:1]
	v_pk_fma_f32 v[54:55], v[138:139], s[28:29], v[54:55] op_sel_hi:[1,0,1]
	v_mov_b32_dpp v128, v136 row_ror:8 row_mask:0xf bank_mask:0xf
	v_and_b32_e32 v129, 64, v221
	v_pk_fma_f32 v[42:43], v[146:147], s[28:29], v[42:43] op_sel_hi:[1,0,1]
	v_cndmask_b32_e64 v136, v128, v154, s[0:1]
	v_cndmask_b32_e64 v138, v130, v128, s[0:1]
	v_xor_b32_e32 v128, 16, v221
	v_add_u32_e32 v129, 64, v129
	v_cmp_lt_i32_e32 vcc, v128, v129
	v_cndmask_b32_e32 v128, v221, v128, vcc
	v_lshlrev_b32_e32 v128, 2, v128
	v_xor_b32_e32 v141, 32, v221
	v_cmp_lt_i32_e32 vcc, v141, v129
	v_cndmask_b32_e64 v137, v155, v131, s[0:1]
	v_mov_b32_e32 v130, v169
	v_cndmask_b32_e32 v129, v221, v141, vcc
	v_lshlrev_b32_e32 v129, 2, v129
	v_mov_b32_dpp v130, v137 row_ror:8 row_mask:0xf bank_mask:0xf
	v_cndmask_b32_e64 v137, v130, v155, s[0:1]
	v_cndmask_b32_e64 v139, v131, v130, s[0:1]
	v_pk_fma_f32 v[58:59], v[136:137], s[28:29], v[58:59] op_sel_hi:[1,0,1]
	v_pk_fma_f32 v[56:57], v[132:133], s[28:29], v[56:57] op_sel_hi:[1,0,1]
	v_pk_fma_f32 v[62:63], v[138:139], s[28:29], v[62:63] op_sel_hi:[1,0,1]
	v_pk_fma_f32 v[60:61], v[134:135], s[28:29], v[60:61] op_sel_hi:[1,0,1]
	v_pk_add_f32 v[236:237], v[92:93], v[94:95]
	v_pk_add_f32 v[238:239], v[96:97], v[98:99]
	v_pk_add_f32 v[240:241], v[100:101], v[102:103]
	v_pk_add_f32 v[242:243], v[108:109], v[110:111]
	v_pk_add_f32 v[236:237], v[236:237], v[238:239]
	v_pk_add_f32 v[240:241], v[240:241], v[242:243]
	s_nop 0
	v_pk_add_f32 v[236:237], v[236:237], v[240:241]
	s_nop 0
	v_add_f32_e32 v236, v236, v237
	v_mov_b32_e32 v237, v236
	s_nop 1
	v_permlane16_swap_b32_e32 v236, v237
	v_add_f32_e32 v236, v236, v237
	v_mov_b32_e32 v237, v236
	s_nop 1
	v_permlane32_swap_b32_e32 v236, v237
	v_add_f32_e32 v236, v236, v237
	v_mul_f32_e32 v238, 0xbc800000, v236
	s_nop 0
	v_pk_add_f32 v[240:241], v[92:93], v[238:239] op_sel_hi:[1,0]
	v_pk_add_f32 v[244:245], v[94:95], v[238:239] op_sel_hi:[1,0]
	v_pk_mul_f32 v[242:243], v[240:241], v[240:241]
	v_pk_mul_f32 v[246:247], v[244:245], v[244:245]
	v_pk_add_f32 v[240:241], v[96:97], v[238:239] op_sel_hi:[1,0]
	v_pk_add_f32 v[244:245], v[98:99], v[238:239] op_sel_hi:[1,0]
	v_pk_fma_f32 v[242:243], v[240:241], v[240:241], v[242:243]
	v_pk_fma_f32 v[246:247], v[244:245], v[244:245], v[246:247]
	v_pk_add_f32 v[240:241], v[100:101], v[238:239] op_sel_hi:[1,0]
	v_pk_add_f32 v[244:245], v[102:103], v[238:239] op_sel_hi:[1,0]
	v_pk_fma_f32 v[242:243], v[240:241], v[240:241], v[242:243]
	v_pk_fma_f32 v[246:247], v[244:245], v[244:245], v[246:247]
	v_pk_add_f32 v[240:241], v[108:109], v[238:239] op_sel_hi:[1,0]
	v_pk_add_f32 v[244:245], v[110:111], v[238:239] op_sel_hi:[1,0]
	v_pk_fma_f32 v[242:243], v[240:241], v[240:241], v[242:243]
	v_pk_fma_f32 v[246:247], v[244:245], v[244:245], v[246:247]
	s_nop 0
	v_pk_add_f32 v[242:243], v[242:243], v[246:247]
	s_nop 0
	v_add_f32_e32 v237, v242, v243
	v_mov_b32_e32 v238, v237
	s_nop 1
	v_permlane16_swap_b32_e32 v237, v238
	v_add_f32_e32 v237, v237, v238
	v_mov_b32_e32 v238, v237
	s_nop 1
	v_permlane32_swap_b32_e32 v237, v238
	v_add_f32_e32 v237, v237, v238
	s_and_saveexec_b64 s[8:9], s[2:3]
	s_cbranch_execz .LBB0_502
	v_mul_f32_e32 v236, 0x3c800000, v236
	ds_write_b64 v222, v[236:237]
